# v55 + top-k importance reductions via DPP quad_perm adds/moves instead of 64 ds_bpermute round trips
# speedup vs baseline: 1.0054x; 1.0054x over previous
.LBB0_668:
	s_mul_i32 s3, s82, 0x600
	v_readlane_b32 s6, v249, 33
	s_mul_hi_u32 s2, s82, 0x600
	v_readlane_b32 s7, v249, 34
	s_add_u32 s3, s6, s3
	s_addc_u32 s6, s7, s2
	s_lshl_b32 s2, s13, 7
	s_add_u32 s2, s3, s2
	s_addc_u32 s3, s6, 0
	s_lshl_b32 s6, s13, 19
	s_lshl_b32 s7, s12, 21
	s_or_b32 s6, s7, s6
	v_readlane_b32 s8, v249, 31
	v_readlane_b32 s9, v249, 32
	s_add_u32 s94, s8, s6
	v_add_u32_e32 v0, s36, v116
	v_mov_b64_e32 v[2:3], s[2:3]
	v_ashrrev_i32_e32 v117, 31, v116
	s_addc_u32 s95, s9, 0
	v_mad_i64_i32 v[2:3], s[6:7], v0, s85, v[2:3]
	v_lshlrev_b32_e32 v0, 1, v108
	v_lshlrev_b64 v[136:137], 13, v[116:117]
	v_lshl_add_u64 v[140:141], v[2:3], 0, v[0:1]
	v_lshl_add_u64 v[2:3], s[94:95], 0, v[136:137]
	s_mov_b32 s37, s83
	v_lshl_add_u64 v[2:3], s[36:37], 1, v[2:3]
	v_lshl_add_u64 v[2:3], v[2:3], 0, v[0:1]
	global_load_dwordx4 v[98:101], v[140:141], off offset:512
	global_load_dwordx4 v[102:105], v[2:3], off
	s_lshl_b64 s[6:7], 2, s79
	s_add_u32 s6, s6, -1
	s_addc_u32 s7, s7, -1
	s_cmp_lt_u32 s79, 63
	s_cselect_b32 s93, s7, -1
	s_cselect_b32 s92, s6, -1
	s_and_b64 vcc, exec, s[4:5]
	v_mov_b64_e32 v[148:149], s[92:93]
	s_mov_b64 s[4:5], s[92:93]
	s_cbranch_vccnz .LBB0_674
	v_xor_b32_e32 v2, 1, v155
	v_cmp_lt_i32_e32 vcc, v2, v157
	s_nop 1
	v_cndmask_b32_e32 v2, v155, v2, vcc
	v_lshlrev_b32_e32 v14, 2, v2
	v_add_f32_dpp v4, v52, v52 quad_perm:[1,0,3,2] row_mask:0xf bank_mask:0xf
	v_add_f32_dpp v8, v50, v50 quad_perm:[1,0,3,2] row_mask:0xf bank_mask:0xf
	v_xor_b32_e32 v2, 2, v155
	v_cmp_lt_i32_e32 vcc, v2, v157
	v_add_f32_dpp v6, v51, v51 quad_perm:[1,0,3,2] row_mask:0xf bank_mask:0xf
	v_add_f32_dpp v10, v152, v152 quad_perm:[1,0,3,2] row_mask:0xf bank_mask:0xf
	v_cndmask_b32_e32 v2, v155, v2, vcc
	v_lshlrev_b32_e32 v15, 2, v2
	v_add_f32_dpp v2, v53, v53 quad_perm:[1,0,3,2] row_mask:0xf bank_mask:0xf
	v_add_f32_dpp v12, v151, v151 quad_perm:[1,0,3,2] row_mask:0xf bank_mask:0xf
	v_add_f32_dpp v16, v147, v147 quad_perm:[1,0,3,2] row_mask:0xf bank_mask:0xf
	v_add_f32_dpp v18, v146, v146 quad_perm:[1,0,3,2] row_mask:0xf bank_mask:0xf
	v_add_f32_dpp v20, v142, v142 quad_perm:[1,0,3,2] row_mask:0xf bank_mask:0xf
	v_add_f32_dpp v22, v143, v143 quad_perm:[1,0,3,2] row_mask:0xf bank_mask:0xf
	v_add_f32_dpp v24, v145, v145 quad_perm:[1,0,3,2] row_mask:0xf bank_mask:0xf
	v_add_f32_dpp v26, v144, v144 quad_perm:[1,0,3,2] row_mask:0xf bank_mask:0xf
	v_add_f32_dpp v28, v131, v131 quad_perm:[1,0,3,2] row_mask:0xf bank_mask:0xf
	v_add_f32_dpp v30, v134, v134 quad_perm:[1,0,3,2] row_mask:0xf bank_mask:0xf
	v_add_f32_dpp v32, v139, v139 quad_perm:[1,0,3,2] row_mask:0xf bank_mask:0xf
	v_add_f32_dpp v50, v138, v138 quad_perm:[1,0,3,2] row_mask:0xf bank_mask:0xf
	v_add_f32_dpp v52, v130, v130 quad_perm:[1,0,3,2] row_mask:0xf bank_mask:0xf
	v_add_f32_dpp v54, v113, v113 quad_perm:[1,0,3,2] row_mask:0xf bank_mask:0xf
	v_add_f32_dpp v56, v133, v133 quad_perm:[1,0,3,2] row_mask:0xf bank_mask:0xf
	v_add_f32_dpp v58, v132, v132 quad_perm:[1,0,3,2] row_mask:0xf bank_mask:0xf
	v_add_f32_dpp v60, v129, v129 quad_perm:[1,0,3,2] row_mask:0xf bank_mask:0xf
	v_add_f32_dpp v62, v125, v125 quad_perm:[1,0,3,2] row_mask:0xf bank_mask:0xf
	v_add_f32_dpp v64, v127, v127 quad_perm:[1,0,3,2] row_mask:0xf bank_mask:0xf
	v_add_f32_dpp v66, v126, v126 quad_perm:[1,0,3,2] row_mask:0xf bank_mask:0xf
	v_add_f32_dpp v68, v128, v128 quad_perm:[1,0,3,2] row_mask:0xf bank_mask:0xf
	v_add_f32_dpp v70, v122, v122 quad_perm:[1,0,3,2] row_mask:0xf bank_mask:0xf
	v_add_f32_dpp v72, v123, v123 quad_perm:[1,0,3,2] row_mask:0xf bank_mask:0xf
	v_add_f32_dpp v74, v124, v124 quad_perm:[1,0,3,2] row_mask:0xf bank_mask:0xf
	v_add_f32_dpp v76, v120, v120 quad_perm:[1,0,3,2] row_mask:0xf bank_mask:0xf
	v_add_f32_dpp v78, v110, v110 quad_perm:[1,0,3,2] row_mask:0xf bank_mask:0xf
	v_add_f32_dpp v80, v111, v111 quad_perm:[1,0,3,2] row_mask:0xf bank_mask:0xf
	v_add_f32_dpp v109, v112, v112 quad_perm:[1,0,3,2] row_mask:0xf bank_mask:0xf
	v_mov_b32_dpp v3, v2 quad_perm:[2,3,0,1] row_mask:0xf bank_mask:0xf
	v_mov_b32_dpp v5, v4 quad_perm:[2,3,0,1] row_mask:0xf bank_mask:0xf
	v_mov_b32_dpp v7, v6 quad_perm:[2,3,0,1] row_mask:0xf bank_mask:0xf
	v_mov_b32_dpp v9, v8 quad_perm:[2,3,0,1] row_mask:0xf bank_mask:0xf
	v_mov_b32_dpp v11, v10 quad_perm:[2,3,0,1] row_mask:0xf bank_mask:0xf
	v_mov_b32_dpp v13, v12 quad_perm:[2,3,0,1] row_mask:0xf bank_mask:0xf
	v_mov_b32_dpp v17, v16 quad_perm:[2,3,0,1] row_mask:0xf bank_mask:0xf
	v_mov_b32_dpp v19, v18 quad_perm:[2,3,0,1] row_mask:0xf bank_mask:0xf
	v_mov_b32_dpp v21, v20 quad_perm:[2,3,0,1] row_mask:0xf bank_mask:0xf
	v_mov_b32_dpp v23, v22 quad_perm:[2,3,0,1] row_mask:0xf bank_mask:0xf
	v_mov_b32_dpp v25, v24 quad_perm:[2,3,0,1] row_mask:0xf bank_mask:0xf
	v_mov_b32_dpp v27, v26 quad_perm:[2,3,0,1] row_mask:0xf bank_mask:0xf
	v_mov_b32_dpp v29, v28 quad_perm:[2,3,0,1] row_mask:0xf bank_mask:0xf
	v_mov_b32_dpp v31, v30 quad_perm:[2,3,0,1] row_mask:0xf bank_mask:0xf
	v_mov_b32_dpp v33, v32 quad_perm:[2,3,0,1] row_mask:0xf bank_mask:0xf
	v_mov_b32_dpp v51, v50 quad_perm:[2,3,0,1] row_mask:0xf bank_mask:0xf
	v_mov_b32_dpp v53, v52 quad_perm:[2,3,0,1] row_mask:0xf bank_mask:0xf
	v_mov_b32_dpp v55, v54 quad_perm:[2,3,0,1] row_mask:0xf bank_mask:0xf
	v_mov_b32_dpp v57, v56 quad_perm:[2,3,0,1] row_mask:0xf bank_mask:0xf
	v_mov_b32_dpp v59, v58 quad_perm:[2,3,0,1] row_mask:0xf bank_mask:0xf
	v_mov_b32_dpp v61, v60 quad_perm:[2,3,0,1] row_mask:0xf bank_mask:0xf
	v_mov_b32_dpp v63, v62 quad_perm:[2,3,0,1] row_mask:0xf bank_mask:0xf
	v_mov_b32_dpp v65, v64 quad_perm:[2,3,0,1] row_mask:0xf bank_mask:0xf
	v_mov_b32_dpp v67, v66 quad_perm:[2,3,0,1] row_mask:0xf bank_mask:0xf
	v_mov_b32_dpp v69, v68 quad_perm:[2,3,0,1] row_mask:0xf bank_mask:0xf
	v_mov_b32_dpp v71, v70 quad_perm:[2,3,0,1] row_mask:0xf bank_mask:0xf
	v_mov_b32_dpp v73, v72 quad_perm:[2,3,0,1] row_mask:0xf bank_mask:0xf
	v_mov_b32_dpp v75, v74 quad_perm:[2,3,0,1] row_mask:0xf bank_mask:0xf
	v_mov_b32_dpp v77, v76 quad_perm:[2,3,0,1] row_mask:0xf bank_mask:0xf
	v_mov_b32_dpp v79, v78 quad_perm:[2,3,0,1] row_mask:0xf bank_mask:0xf
	v_mov_b32_dpp v81, v80 quad_perm:[2,3,0,1] row_mask:0xf bank_mask:0xf
	v_mov_b32_dpp v110, v109 quad_perm:[2,3,0,1] row_mask:0xf bank_mask:0xf
	v_cmp_eq_u32_e32 vcc, 0, v171
	s_and_saveexec_b64 s[6:7], vcc
	s_cbranch_execz .LBB0_671
	v_add_f32_e32 v4, v4, v5
	v_add_f32_e32 v2, v2, v3
	v_and_b32_e32 v2, 0xffffffc0, v2
	v_and_b32_e32 v4, 0xffffffc0, v4
	v_lshlrev_b32_e32 v3, 8, v169
	v_readlane_b32 s4, v249, 53
	v_cndmask_b32_e64 v2, v2, v161, s[0:1]
	v_sub_u32_e32 v4, v4, v170
	v_add_f32_e32 v8, v8, v9
	v_add_f32_e32 v6, v6, v7
	v_add3_u32 v3, s4, v3, v119
	v_bitop3_b32 v2, v170, 63, v2 bitop3:0x36
	v_add_u32_e32 v4, 61, v4
	ds_write2_b32 v3, v2, v4 offset1:2
	v_and_b32_e32 v2, 0xffffffc0, v6
	v_and_b32_e32 v4, 0xffffffc0, v8
	v_sub_u32_e32 v2, v2, v170
	v_sub_u32_e32 v4, v4, v170
	v_add_f32_e32 v12, v12, v13
	v_add_f32_e32 v10, v10, v11
	v_add_u32_e32 v2, 59, v2
	v_add_u32_e32 v4, 57, v4
	ds_write2_b32 v3, v2, v4 offset0:4 offset1:6
	v_and_b32_e32 v2, 0xffffffc0, v10
	v_and_b32_e32 v4, 0xffffffc0, v12
	v_sub_u32_e32 v2, v2, v170
	v_sub_u32_e32 v4, v4, v170
	v_add_f32_e32 v18, v18, v19
	v_add_f32_e32 v16, v16, v17
	v_add_u32_e32 v2, 55, v2
	v_add_u32_e32 v4, 53, v4
	s_add_i32 s0, s79, -15
	ds_write2_b32 v3, v2, v4 offset0:8 offset1:10
	v_and_b32_e32 v2, 0xffffffc0, v16
	v_and_b32_e32 v4, 0xffffffc0, v18
	v_cmp_ne_u32_e32 vcc, s0, v170
	v_sub_u32_e32 v2, v2, v170
	v_add_u32_e32 v2, 51, v2
	v_cndmask_b32_e32 v4, v161, v4, vcc
	v_bitop3_b32 v4, v170, 49, v4 bitop3:0x36
	v_add_f32_e32 v20, v20, v21
	s_add_i32 s8, s79, -1
	ds_write2_b32 v3, v2, v4 offset0:12 offset1:14
	v_or_b32_e32 v2, 16, v170
	v_cmp_eq_u32_e32 vcc, s79, v2
	v_cmp_eq_u32_e64 s[0:1], s8, v2
	v_and_b32_e32 v4, 0xffffffc0, v20
	v_cmp_ge_u32_e64 s[4:5], s79, v2
	v_add_f32_e32 v22, v22, v23
	s_or_b64 vcc, vcc, s[0:1]
	v_cndmask_b32_e64 v2, 0, v4, s[4:5]
	v_or_b32_e32 v4, 18, v170
	v_cndmask_b32_e32 v2, v2, v161, vcc
	v_cmp_eq_u32_e32 vcc, s79, v4
	v_cmp_eq_u32_e64 s[0:1], s8, v4
	v_and_b32_e32 v5, 0xffffffc0, v22
	v_cmp_ge_u32_e64 s[4:5], s79, v4
	s_or_b64 vcc, vcc, s[0:1]
	v_bitop3_b32 v2, v170, 47, v2 bitop3:0x36
	v_cndmask_b32_e64 v4, 0, v5, s[4:5]
	v_cndmask_b32_e32 v4, v4, v161, vcc
	v_bitop3_b32 v4, v170, 45, v4 bitop3:0x36
	v_add_f32_e32 v24, v24, v25
	ds_write2_b32 v3, v2, v4 offset0:16 offset1:18
	v_or_b32_e32 v2, 20, v170
	v_cmp_eq_u32_e32 vcc, s79, v2
	v_cmp_eq_u32_e64 s[0:1], s8, v2
	v_and_b32_e32 v4, 0xffffffc0, v24
	v_cmp_ge_u32_e64 s[4:5], s79, v2
	v_add_f32_e32 v26, v26, v27
	s_or_b64 vcc, vcc, s[0:1]
	v_cndmask_b32_e64 v2, 0, v4, s[4:5]
	v_or_b32_e32 v4, 22, v170
	v_cndmask_b32_e32 v2, v2, v161, vcc
	v_cmp_eq_u32_e32 vcc, s79, v4
	v_cmp_eq_u32_e64 s[0:1], s8, v4
	v_and_b32_e32 v5, 0xffffffc0, v26
	v_cmp_ge_u32_e64 s[4:5], s79, v4
	s_or_b64 vcc, vcc, s[0:1]
	v_bitop3_b32 v2, v170, 43, v2 bitop3:0x36
	v_cndmask_b32_e64 v4, 0, v5, s[4:5]
	v_cndmask_b32_e32 v4, v4, v161, vcc
	v_bitop3_b32 v4, v170, 41, v4 bitop3:0x36
	v_add_f32_e32 v28, v28, v29
	ds_write2_b32 v3, v2, v4 offset0:20 offset1:22
	v_or_b32_e32 v2, 24, v170
	v_cmp_eq_u32_e32 vcc, s79, v2
	v_cmp_eq_u32_e64 s[0:1], s8, v2
	v_and_b32_e32 v4, 0xffffffc0, v28
	v_cmp_ge_u32_e64 s[4:5], s79, v2
	v_add_f32_e32 v30, v30, v31
	s_or_b64 vcc, vcc, s[0:1]
	v_cndmask_b32_e64 v2, 0, v4, s[4:5]
	v_or_b32_e32 v4, 26, v170
	v_cndmask_b32_e32 v2, v2, v161, vcc
	v_cmp_eq_u32_e32 vcc, s79, v4
	v_cmp_eq_u32_e64 s[0:1], s8, v4
	v_and_b32_e32 v5, 0xffffffc0, v30
	v_cmp_ge_u32_e64 s[4:5], s79, v4
	s_or_b64 vcc, vcc, s[0:1]
	v_bitop3_b32 v2, v170, 39, v2 bitop3:0x36
	v_cndmask_b32_e64 v4, 0, v5, s[4:5]
	v_cndmask_b32_e32 v4, v4, v161, vcc
	v_bitop3_b32 v4, v170, 37, v4 bitop3:0x36
	v_add_f32_e32 v32, v32, v33
	ds_write2_b32 v3, v2, v4 offset0:24 offset1:26
	v_or_b32_e32 v2, 28, v170
	v_cmp_eq_u32_e32 vcc, s79, v2
	v_cmp_eq_u32_e64 s[0:1], s8, v2
	v_and_b32_e32 v4, 0xffffffc0, v32
	v_cmp_ge_u32_e64 s[4:5], s79, v2
	v_add_f32_e32 v50, v50, v51
	s_or_b64 vcc, vcc, s[0:1]
	v_cndmask_b32_e64 v2, 0, v4, s[4:5]
	v_or_b32_e32 v4, 30, v170
	v_cndmask_b32_e32 v2, v2, v161, vcc
	v_cmp_eq_u32_e32 vcc, s79, v4
	v_cmp_eq_u32_e64 s[0:1], s8, v4
	v_and_b32_e32 v5, 0xffffffc0, v50
	v_cmp_ge_u32_e64 s[4:5], s79, v4
	s_or_b64 vcc, vcc, s[0:1]
	v_bitop3_b32 v2, v170, 35, v2 bitop3:0x36
	v_cndmask_b32_e64 v4, 0, v5, s[4:5]
	v_cndmask_b32_e32 v4, v4, v161, vcc
	v_bitop3_b32 v4, v170, 33, v4 bitop3:0x36
	v_add_f32_e32 v52, v52, v53
	ds_write2_b32 v3, v2, v4 offset0:28 offset1:30
	v_or_b32_e32 v2, 32, v170
	v_cmp_eq_u32_e32 vcc, s79, v2
	v_cmp_eq_u32_e64 s[0:1], s8, v2
	v_and_b32_e32 v4, 0xffffffc0, v52
	v_cmp_ge_u32_e64 s[4:5], s79, v2
	v_add_f32_e32 v54, v54, v55
	s_or_b64 vcc, vcc, s[0:1]
	v_cndmask_b32_e64 v2, 0, v4, s[4:5]
	v_or_b32_e32 v4, 34, v170
	v_cndmask_b32_e32 v2, v2, v161, vcc
	v_cmp_eq_u32_e32 vcc, s79, v4
	v_cmp_eq_u32_e64 s[0:1], s8, v4
	v_and_b32_e32 v5, 0xffffffc0, v54
	v_cmp_ge_u32_e64 s[4:5], s79, v4
	s_or_b64 vcc, vcc, s[0:1]
	v_bitop3_b32 v2, v170, 31, v2 bitop3:0x36
	v_cndmask_b32_e64 v4, 0, v5, s[4:5]
	v_cndmask_b32_e32 v4, v4, v161, vcc
	v_bitop3_b32 v4, v170, 29, v4 bitop3:0x36
	v_add_f32_e32 v56, v56, v57
	ds_write2_b32 v3, v2, v4 offset0:32 offset1:34
	v_or_b32_e32 v2, 36, v170
	v_cmp_eq_u32_e32 vcc, s79, v2
	v_cmp_eq_u32_e64 s[0:1], s8, v2
	v_and_b32_e32 v4, 0xffffffc0, v56
	v_cmp_ge_u32_e64 s[4:5], s79, v2
	v_add_f32_e32 v58, v58, v59
	s_or_b64 vcc, vcc, s[0:1]
	v_cndmask_b32_e64 v2, 0, v4, s[4:5]
	v_or_b32_e32 v4, 38, v170
	v_cndmask_b32_e32 v2, v2, v161, vcc
	v_cmp_eq_u32_e32 vcc, s79, v4
	v_cmp_eq_u32_e64 s[0:1], s8, v4
	v_and_b32_e32 v5, 0xffffffc0, v58
	v_cmp_ge_u32_e64 s[4:5], s79, v4
	s_or_b64 vcc, vcc, s[0:1]
	v_bitop3_b32 v2, v170, 27, v2 bitop3:0x36
	v_cndmask_b32_e64 v4, 0, v5, s[4:5]
	v_cndmask_b32_e32 v4, v4, v161, vcc
	v_bitop3_b32 v4, v170, 25, v4 bitop3:0x36
	v_add_f32_e32 v60, v60, v61
	ds_write2_b32 v3, v2, v4 offset0:36 offset1:38
	v_or_b32_e32 v2, 40, v170
	v_cmp_eq_u32_e32 vcc, s79, v2
	v_cmp_eq_u32_e64 s[0:1], s8, v2
	v_and_b32_e32 v4, 0xffffffc0, v60
	v_cmp_ge_u32_e64 s[4:5], s79, v2
	v_add_f32_e32 v62, v62, v63
	s_or_b64 vcc, vcc, s[0:1]
	v_cndmask_b32_e64 v2, 0, v4, s[4:5]
	v_or_b32_e32 v4, 42, v170
	v_cndmask_b32_e32 v2, v2, v161, vcc
	v_cmp_eq_u32_e32 vcc, s79, v4
	v_cmp_eq_u32_e64 s[0:1], s8, v4
	v_and_b32_e32 v5, 0xffffffc0, v62
	v_cmp_ge_u32_e64 s[4:5], s79, v4
	s_or_b64 vcc, vcc, s[0:1]
	v_bitop3_b32 v2, v170, 23, v2 bitop3:0x36
	v_cndmask_b32_e64 v4, 0, v5, s[4:5]
	v_cndmask_b32_e32 v4, v4, v161, vcc
	v_bitop3_b32 v4, v170, 21, v4 bitop3:0x36
	v_add_f32_e32 v64, v64, v65
	ds_write2_b32 v3, v2, v4 offset0:40 offset1:42
	v_or_b32_e32 v2, 44, v170
	v_cmp_eq_u32_e32 vcc, s79, v2
	v_cmp_eq_u32_e64 s[0:1], s8, v2
	v_and_b32_e32 v4, 0xffffffc0, v64
	v_cmp_ge_u32_e64 s[4:5], s79, v2
	v_add_f32_e32 v66, v66, v67
	s_or_b64 vcc, vcc, s[0:1]
	v_cndmask_b32_e64 v2, 0, v4, s[4:5]
	v_or_b32_e32 v4, 46, v170
	v_cndmask_b32_e32 v2, v2, v161, vcc
	v_cmp_eq_u32_e32 vcc, s79, v4
	v_cmp_eq_u32_e64 s[0:1], s8, v4
	v_and_b32_e32 v5, 0xffffffc0, v66
	v_cmp_ge_u32_e64 s[4:5], s79, v4
	s_or_b64 vcc, vcc, s[0:1]
	v_bitop3_b32 v2, v170, 19, v2 bitop3:0x36
	v_cndmask_b32_e64 v4, 0, v5, s[4:5]
	v_cndmask_b32_e32 v4, v4, v161, vcc
	v_bitop3_b32 v4, v170, 17, v4 bitop3:0x36
	v_add_f32_e32 v68, v68, v69
	ds_write2_b32 v3, v2, v4 offset0:44 offset1:46
	v_or_b32_e32 v2, 48, v170
	v_cmp_eq_u32_e32 vcc, s79, v2
	v_cmp_eq_u32_e64 s[0:1], s8, v2
	v_and_b32_e32 v4, 0xffffffc0, v68
	v_cmp_ge_u32_e64 s[4:5], s79, v2
	v_add_f32_e32 v70, v70, v71
	s_or_b64 vcc, vcc, s[0:1]
	v_cndmask_b32_e64 v2, 0, v4, s[4:5]
	v_or_b32_e32 v4, 50, v170
	v_cndmask_b32_e32 v2, v2, v161, vcc
	v_cmp_eq_u32_e32 vcc, s79, v4
	v_cmp_eq_u32_e64 s[0:1], s8, v4
	v_and_b32_e32 v5, 0xffffffc0, v70
	v_cmp_ge_u32_e64 s[4:5], s79, v4
	s_or_b64 vcc, vcc, s[0:1]
	v_bitop3_b32 v2, v170, 15, v2 bitop3:0x36
	v_cndmask_b32_e64 v4, 0, v5, s[4:5]
	v_cndmask_b32_e32 v4, v4, v161, vcc
	v_bitop3_b32 v4, v170, 13, v4 bitop3:0x36
	v_add_f32_e32 v72, v72, v73
	ds_write2_b32 v3, v2, v4 offset0:48 offset1:50
	v_or_b32_e32 v2, 52, v170
	v_cmp_eq_u32_e32 vcc, s79, v2
	v_cmp_eq_u32_e64 s[0:1], s8, v2
	v_and_b32_e32 v4, 0xffffffc0, v72
	v_cmp_ge_u32_e64 s[4:5], s79, v2
	v_add_f32_e32 v74, v74, v75
	s_or_b64 vcc, vcc, s[0:1]
	v_cndmask_b32_e64 v2, 0, v4, s[4:5]
	v_or_b32_e32 v4, 54, v170
	v_cndmask_b32_e32 v2, v2, v161, vcc
	v_cmp_eq_u32_e32 vcc, s79, v4
	v_cmp_eq_u32_e64 s[0:1], s8, v4
	v_and_b32_e32 v5, 0xffffffc0, v74
	v_cmp_ge_u32_e64 s[4:5], s79, v4
	s_or_b64 vcc, vcc, s[0:1]
	v_bitop3_b32 v2, v170, 11, v2 bitop3:0x36
	v_cndmask_b32_e64 v4, 0, v5, s[4:5]
	v_cndmask_b32_e32 v4, v4, v161, vcc
	v_bitop3_b32 v4, v170, 9, v4 bitop3:0x36
	v_add_f32_e32 v76, v76, v77
	ds_write2_b32 v3, v2, v4 offset0:52 offset1:54
	v_or_b32_e32 v2, 56, v170
	v_cmp_eq_u32_e32 vcc, s79, v2
	v_cmp_eq_u32_e64 s[0:1], s8, v2
	v_and_b32_e32 v4, 0xffffffc0, v76
	v_cmp_ge_u32_e64 s[4:5], s79, v2
	v_add_f32_e32 v78, v78, v79
	s_or_b64 vcc, vcc, s[0:1]
	v_cndmask_b32_e64 v2, 0, v4, s[4:5]
	v_or_b32_e32 v4, 58, v170
	v_cndmask_b32_e32 v2, v2, v161, vcc
	v_cmp_eq_u32_e32 vcc, s79, v4
	v_cmp_eq_u32_e64 s[0:1], s8, v4
	v_and_b32_e32 v5, 0xffffffc0, v78
	v_cmp_ge_u32_e64 s[4:5], s79, v4
	s_or_b64 vcc, vcc, s[0:1]
	v_bitop3_b32 v2, v170, 7, v2 bitop3:0x36
	v_cndmask_b32_e64 v4, 0, v5, s[4:5]
	v_cndmask_b32_e32 v4, v4, v161, vcc
	v_bitop3_b32 v4, v170, 5, v4 bitop3:0x36
	v_add_f32_e32 v80, v80, v81
	ds_write2_b32 v3, v2, v4 offset0:56 offset1:58
	v_or_b32_e32 v2, 60, v170
	v_cmp_eq_u32_e32 vcc, s79, v2
	v_cmp_eq_u32_e64 s[0:1], s8, v2
	v_and_b32_e32 v4, 0xffffffc0, v80
	v_cmp_ge_u32_e64 s[4:5], s79, v2
	v_add_f32_e32 v109, v109, v110
	s_or_b64 vcc, vcc, s[0:1]
	v_cndmask_b32_e64 v2, 0, v4, s[4:5]
	v_or_b32_e32 v4, 62, v170
	v_cndmask_b32_e32 v2, v2, v161, vcc
	v_cmp_eq_u32_e32 vcc, s79, v4
	v_cmp_eq_u32_e64 s[0:1], s8, v4
	v_and_b32_e32 v5, 0xffffffc0, v109
	v_cmp_ge_u32_e64 s[4:5], s79, v4
	s_or_b64 vcc, vcc, s[0:1]
	v_bitop3_b32 v2, v170, 3, v2 bitop3:0x36
	v_cndmask_b32_e64 v4, 0, v5, s[4:5]
	v_cndmask_b32_e32 v4, v4, v161, vcc
	v_bitop3_b32 v4, v170, 1, v4 bitop3:0x36
	ds_write2_b32 v3, v2, v4 offset0:60 offset1:62
